# gdn_pre S5: blocked inversion (16x16 substitution blocks on one wave + f32 MFMA 16x16x4 block products on all 4 waves of the half) replaces the single-wave 64-row substitution
# speedup vs baseline: 1.0146x; 1.0100x over previous
.LBB0_226:
	v_readlane_b32 s8, v242, 9
	v_and_b32_e32 v0, 15, v152
	v_lshrrev_b32_e32 v1, 4, v152
	s_and_b32 s9, s8, 3
	s_lshr_b32 s42, s8, 2
	s_and_b32 s43, s8, 1
	s_xor_b32 s43, s43, 1
	s_and_b32 s43, s43, s42
	s_lshl_b32 s43, s43, 1
	s_xor_b32 s9, s9, s43
	v_lshlrev_b32_e32 v2, 8, v0
	v_lshl_add_u32 v2, v1, 4, v2
	v_add_u32_e32 v2, s19, v2
	v_lshlrev_b32_e32 v3, 2, v0
	v_lshl_add_u32 v3, v1, 10, v3
	v_add_u32_e32 v3, s19, v3
	v_mul_u32_u24_e32 v4, 0x240, v1
	v_lshl_add_u32 v4, v0, 1, v4
	v_add_u32_e32 v4, s19, v4
	s_cmp_eq_u32 s9, 0
	s_cbranch_scc1 .Linv_r0
	s_cmp_eq_u32 s9, 2
	s_cbranch_scc0 .Linv_A
.Linv_r2:
	v_lshrrev_b32_e32 v9, 2, v152
	v_mul_u32_u24_e32 v9, 0x90, v9
	v_and_b32_e32 v10, 3, v152
	v_lshl_add_u32 v9, v10, 3, v9
	v_add_u32_e32 v9, s19, v9
	v_mov_b32_e32 v10, 0
	v_mov_b32_e32 v11, 0
	ds_write_b64 v9, v[10:11] offset:32
	ds_write_b64 v9, v[10:11] offset:64
	ds_write_b64 v9, v[10:11] offset:96
	ds_write_b64 v9, v[10:11] offset:2368
	ds_write_b64 v9, v[10:11] offset:2400
	ds_write_b64 v9, v[10:11] offset:4704
	s_branch .Linv_A
.Linv_r0:
	v_mul_u32_u24_e32 v5, 0x1040, v1
	v_add_u32_e32 v5, s19, v5
	v_lshl_add_u32 v6, v0, 8, v5
	v_lshlrev_b32_e32 v7, 6, v1
	v_lshl_add_u32 v7, v0, 2, v7
	v_add_u32_e32 v7, s19, v7
	v_mul_u32_u24_e32 v8, 0x920, v1
	v_lshl_add_u32 v8, v0, 1, v8
	v_add_u32_e32 v8, s19, v8
	v_mov_b64_e32 v[98:99], 0
	v_mov_b64_e32 v[100:101], 0
	v_mov_b64_e32 v[102:103], 0
	v_mov_b64_e32 v[104:105], 0
	v_mov_b64_e32 v[106:107], 0
	v_mov_b64_e32 v[108:109], 0
	v_mov_b64_e32 v[110:111], 0
	v_mov_b64_e32 v[112:113], 0
	v_mov_b32_e32 v15, 0
	ds_read_b128 v[34:37], v5 offset:17664
	ds_read_b128 v[38:41], v5 offset:17920
	ds_read_b128 v[42:45], v5 offset:18176
	ds_read_b128 v[46:49], v5 offset:18432
	ds_read_b128 v[50:53], v5 offset:18688
	ds_read_b128 v[54:57], v5 offset:18704
	ds_read_b128 v[58:61], v5 offset:18944
	ds_read_b128 v[62:65], v5 offset:18960
	ds_read_b128 v[66:69], v5 offset:19200
	ds_read_b128 v[70:73], v5 offset:19216
	ds_read_b128 v[74:77], v5 offset:19456
	ds_read_b128 v[78:81], v5 offset:19472
	ds_read_b128 v[162:165], v5 offset:19712
	ds_read_b128 v[166:169], v5 offset:19728
	v_cmp_eq_u32_e32 vcc, 0, v0
	s_nop 1
	v_cndmask_b32_e64 v98, 0, 1.0, vcc
	v_cmp_eq_u32_e32 vcc, 1, v0
	v_cvt_pk_bf16_f32 v12, v98, v98
	ds_write_b16 v8, v12 offset:0
	v_cndmask_b32_e64 v14, 0, 1.0, vcc
	ds_read_b128 v[170:173], v5 offset:19744
	ds_read_b128 v[174:177], v5 offset:19968
	s_waitcnt lgkmcnt(15)
	v_pk_fma_f32 v[16:17], v[34:35], v[98:99], v[14:15] neg_lo:[1,0,0] neg_hi:[1,0,0]
	v_pk_fma_f32 v[22:23], v[36:37], v[100:101], 0 neg_lo:[1,0,0] neg_hi:[1,0,0]
	v_cmp_eq_u32_e32 vcc, 2, v0
	v_pk_add_f32 v[18:19], v[16:17], v[22:23]
	v_add_f32_e32 v99, v18, v19
	v_cvt_pk_bf16_f32 v12, v99, v99
	ds_write_b16 v8, v12 offset:144
	v_cndmask_b32_e64 v14, 0, 1.0, vcc
	ds_read_b128 v[178:181], v5 offset:19984
	ds_read_b128 v[182:185], v5 offset:20000
	s_waitcnt lgkmcnt(15)
	v_pk_fma_f32 v[16:17], v[38:39], v[98:99], v[14:15] neg_lo:[1,0,0] neg_hi:[1,0,0]
	v_pk_fma_f32 v[22:23], v[40:41], v[100:101], 0 neg_lo:[1,0,0] neg_hi:[1,0,0]
	v_cmp_eq_u32_e32 vcc, 3, v0
	v_pk_add_f32 v[18:19], v[16:17], v[22:23]
	v_add_f32_e32 v100, v18, v19
	v_cvt_pk_bf16_f32 v12, v100, v100
	ds_write_b16 v8, v12 offset:288
	v_cndmask_b32_e64 v14, 0, 1.0, vcc
	ds_read_b128 v[186:189], v5 offset:20224
	ds_read_b128 v[198:201], v5 offset:20240
	s_waitcnt lgkmcnt(15)
	v_pk_fma_f32 v[16:17], v[42:43], v[98:99], v[14:15] neg_lo:[1,0,0] neg_hi:[1,0,0]
	v_pk_fma_f32 v[22:23], v[44:45], v[100:101], 0 neg_lo:[1,0,0] neg_hi:[1,0,0]
	v_cmp_eq_u32_e32 vcc, 4, v0
	v_pk_add_f32 v[18:19], v[16:17], v[22:23]
	v_add_f32_e32 v101, v18, v19
	v_cvt_pk_bf16_f32 v12, v101, v101
	ds_write_b16 v8, v12 offset:432
	v_cndmask_b32_e64 v14, 0, 1.0, vcc
	ds_read_b128 v[202:205], v5 offset:20256
	ds_read_b128 v[206:209], v5 offset:20480
	s_waitcnt lgkmcnt(15)
	v_pk_fma_f32 v[16:17], v[46:47], v[98:99], v[14:15] neg_lo:[1,0,0] neg_hi:[1,0,0]
	v_pk_fma_f32 v[22:23], v[48:49], v[100:101], 0 neg_lo:[1,0,0] neg_hi:[1,0,0]
	v_cmp_eq_u32_e32 vcc, 5, v0
	v_pk_add_f32 v[18:19], v[16:17], v[22:23]
	v_add_f32_e32 v102, v18, v19
	v_cvt_pk_bf16_f32 v12, v102, v102
	ds_write_b16 v8, v12 offset:576
	v_cndmask_b32_e64 v14, 0, 1.0, vcc
	ds_read_b128 v[138:141], v5 offset:20496
	ds_read_b128 v[154:157], v5 offset:20512
	ds_read_b128 v[86:89], v5 offset:20736
	s_waitcnt lgkmcnt(15)
	v_pk_fma_f32 v[16:17], v[50:51], v[98:99], v[14:15] neg_lo:[1,0,0] neg_hi:[1,0,0]
	v_pk_fma_f32 v[22:23], v[52:53], v[100:101], 0 neg_lo:[1,0,0] neg_hi:[1,0,0]
	s_waitcnt lgkmcnt(15)
	v_pk_fma_f32 v[16:17], v[54:55], v[102:103], v[16:17] neg_lo:[1,0,0] neg_hi:[1,0,0]
	v_pk_fma_f32 v[22:23], v[56:57], v[104:105], v[22:23] neg_lo:[1,0,0] neg_hi:[1,0,0]
	v_cmp_eq_u32_e32 vcc, 6, v0
	v_pk_add_f32 v[18:19], v[16:17], v[22:23]
	v_add_f32_e32 v103, v18, v19
	v_cvt_pk_bf16_f32 v12, v103, v103
	ds_write_b16 v8, v12 offset:720
	v_cndmask_b32_e64 v14, 0, 1.0, vcc
	ds_read_b128 v[190:193], v5 offset:20752
	ds_read_b128 v[210:213], v5 offset:20768
	ds_read_b128 v[90:93], v5 offset:20784
	s_waitcnt lgkmcnt(15)
	v_pk_fma_f32 v[16:17], v[58:59], v[98:99], v[14:15] neg_lo:[1,0,0] neg_hi:[1,0,0]
	v_pk_fma_f32 v[22:23], v[60:61], v[100:101], 0 neg_lo:[1,0,0] neg_hi:[1,0,0]
	s_waitcnt lgkmcnt(15)
	v_pk_fma_f32 v[16:17], v[62:63], v[102:103], v[16:17] neg_lo:[1,0,0] neg_hi:[1,0,0]
	v_pk_fma_f32 v[22:23], v[64:65], v[104:105], v[22:23] neg_lo:[1,0,0] neg_hi:[1,0,0]
	v_cmp_eq_u32_e32 vcc, 7, v0
	v_pk_add_f32 v[18:19], v[16:17], v[22:23]
	v_add_f32_e32 v104, v18, v19
	v_cvt_pk_bf16_f32 v12, v104, v104
	ds_write_b16 v8, v12 offset:864
	v_cndmask_b32_e64 v14, 0, 1.0, vcc
	ds_read_b128 v[26:29], v5 offset:20992
	ds_read_b128 v[34:37], v5 offset:21008
	ds_read_b128 v[38:41], v5 offset:21024
	s_waitcnt lgkmcnt(15)
	v_pk_fma_f32 v[16:17], v[66:67], v[98:99], v[14:15] neg_lo:[1,0,0] neg_hi:[1,0,0]
	v_pk_fma_f32 v[22:23], v[68:69], v[100:101], 0 neg_lo:[1,0,0] neg_hi:[1,0,0]
	s_waitcnt lgkmcnt(15)
	v_pk_fma_f32 v[16:17], v[70:71], v[102:103], v[16:17] neg_lo:[1,0,0] neg_hi:[1,0,0]
	v_pk_fma_f32 v[22:23], v[72:73], v[104:105], v[22:23] neg_lo:[1,0,0] neg_hi:[1,0,0]
	v_cmp_eq_u32_e32 vcc, 8, v0
	v_pk_add_f32 v[18:19], v[16:17], v[22:23]
	v_add_f32_e32 v105, v18, v19
	v_cvt_pk_bf16_f32 v12, v105, v105
	ds_write_b16 v8, v12 offset:1008
	v_cndmask_b32_e64 v14, 0, 1.0, vcc
	ds_read_b128 v[42:45], v5 offset:21040
	ds_read_b128 v[46:49], v5 offset:21248
	ds_read_b128 v[50:53], v5 offset:21264
	s_waitcnt lgkmcnt(15)
	v_pk_fma_f32 v[16:17], v[74:75], v[98:99], v[14:15] neg_lo:[1,0,0] neg_hi:[1,0,0]
	v_pk_fma_f32 v[22:23], v[76:77], v[100:101], 0 neg_lo:[1,0,0] neg_hi:[1,0,0]
	s_waitcnt lgkmcnt(15)
	v_pk_fma_f32 v[16:17], v[78:79], v[102:103], v[16:17] neg_lo:[1,0,0] neg_hi:[1,0,0]
	v_pk_fma_f32 v[22:23], v[80:81], v[104:105], v[22:23] neg_lo:[1,0,0] neg_hi:[1,0,0]
	v_cmp_eq_u32_e32 vcc, 9, v0
	v_pk_add_f32 v[18:19], v[16:17], v[22:23]
	v_add_f32_e32 v106, v18, v19
	v_cvt_pk_bf16_f32 v12, v106, v106
	ds_write_b16 v8, v12 offset:1152
	v_cndmask_b32_e64 v14, 0, 1.0, vcc
	ds_read_b128 v[54:57], v5 offset:21280
	ds_read_b128 v[58:61], v5 offset:21296
	s_waitcnt lgkmcnt(15)
	v_pk_fma_f32 v[16:17], v[162:163], v[98:99], v[14:15] neg_lo:[1,0,0] neg_hi:[1,0,0]
	v_pk_fma_f32 v[22:23], v[164:165], v[100:101], 0 neg_lo:[1,0,0] neg_hi:[1,0,0]
	s_waitcnt lgkmcnt(15)
	v_pk_fma_f32 v[16:17], v[166:167], v[102:103], v[16:17] neg_lo:[1,0,0] neg_hi:[1,0,0]
	v_pk_fma_f32 v[22:23], v[168:169], v[104:105], v[22:23] neg_lo:[1,0,0] neg_hi:[1,0,0]
	s_waitcnt lgkmcnt(15)
	v_pk_fma_f32 v[16:17], v[170:171], v[106:107], v[16:17] neg_lo:[1,0,0] neg_hi:[1,0,0]
	v_pk_fma_f32 v[22:23], v[172:173], v[108:109], v[22:23] neg_lo:[1,0,0] neg_hi:[1,0,0]
	v_cmp_eq_u32_e32 vcc, 10, v0
	v_pk_add_f32 v[18:19], v[16:17], v[22:23]
	v_add_f32_e32 v107, v18, v19
	v_cvt_pk_bf16_f32 v12, v107, v107
	ds_write_b16 v8, v12 offset:1296
	v_cndmask_b32_e64 v14, 0, 1.0, vcc
	s_waitcnt lgkmcnt(15)
	v_pk_fma_f32 v[16:17], v[174:175], v[98:99], v[14:15] neg_lo:[1,0,0] neg_hi:[1,0,0]
	v_pk_fma_f32 v[22:23], v[176:177], v[100:101], 0 neg_lo:[1,0,0] neg_hi:[1,0,0]
	s_waitcnt lgkmcnt(15)
	v_pk_fma_f32 v[16:17], v[178:179], v[102:103], v[16:17] neg_lo:[1,0,0] neg_hi:[1,0,0]
	v_pk_fma_f32 v[22:23], v[180:181], v[104:105], v[22:23] neg_lo:[1,0,0] neg_hi:[1,0,0]
	s_waitcnt lgkmcnt(15)
	v_pk_fma_f32 v[16:17], v[182:183], v[106:107], v[16:17] neg_lo:[1,0,0] neg_hi:[1,0,0]
	v_pk_fma_f32 v[22:23], v[184:185], v[108:109], v[22:23] neg_lo:[1,0,0] neg_hi:[1,0,0]
	v_cmp_eq_u32_e32 vcc, 11, v0
	v_pk_add_f32 v[18:19], v[16:17], v[22:23]
	v_add_f32_e32 v108, v18, v19
	v_cvt_pk_bf16_f32 v12, v108, v108
	ds_write_b16 v8, v12 offset:1440
	v_cndmask_b32_e64 v14, 0, 1.0, vcc
	s_waitcnt lgkmcnt(15)
	v_pk_fma_f32 v[16:17], v[186:187], v[98:99], v[14:15] neg_lo:[1,0,0] neg_hi:[1,0,0]
	v_pk_fma_f32 v[22:23], v[188:189], v[100:101], 0 neg_lo:[1,0,0] neg_hi:[1,0,0]
	s_waitcnt lgkmcnt(15)
	v_pk_fma_f32 v[16:17], v[198:199], v[102:103], v[16:17] neg_lo:[1,0,0] neg_hi:[1,0,0]
	v_pk_fma_f32 v[22:23], v[200:201], v[104:105], v[22:23] neg_lo:[1,0,0] neg_hi:[1,0,0]
	s_waitcnt lgkmcnt(15)
	v_pk_fma_f32 v[16:17], v[202:203], v[106:107], v[16:17] neg_lo:[1,0,0] neg_hi:[1,0,0]
	v_pk_fma_f32 v[22:23], v[204:205], v[108:109], v[22:23] neg_lo:[1,0,0] neg_hi:[1,0,0]
	v_cmp_eq_u32_e32 vcc, 12, v0
	v_pk_add_f32 v[18:19], v[16:17], v[22:23]
	v_add_f32_e32 v109, v18, v19
	v_cvt_pk_bf16_f32 v12, v109, v109
	ds_write_b16 v8, v12 offset:1584
	v_cndmask_b32_e64 v14, 0, 1.0, vcc
	s_waitcnt lgkmcnt(15)
	v_pk_fma_f32 v[16:17], v[206:207], v[98:99], v[14:15] neg_lo:[1,0,0] neg_hi:[1,0,0]
	v_pk_fma_f32 v[22:23], v[208:209], v[100:101], 0 neg_lo:[1,0,0] neg_hi:[1,0,0]
	s_waitcnt lgkmcnt(15)
	v_pk_fma_f32 v[16:17], v[138:139], v[102:103], v[16:17] neg_lo:[1,0,0] neg_hi:[1,0,0]
	v_pk_fma_f32 v[22:23], v[140:141], v[104:105], v[22:23] neg_lo:[1,0,0] neg_hi:[1,0,0]
	s_waitcnt lgkmcnt(15)
	v_pk_fma_f32 v[16:17], v[154:155], v[106:107], v[16:17] neg_lo:[1,0,0] neg_hi:[1,0,0]
	v_pk_fma_f32 v[22:23], v[156:157], v[108:109], v[22:23] neg_lo:[1,0,0] neg_hi:[1,0,0]
	v_cmp_eq_u32_e32 vcc, 13, v0
	v_pk_add_f32 v[18:19], v[16:17], v[22:23]
	v_add_f32_e32 v110, v18, v19
	v_cvt_pk_bf16_f32 v12, v110, v110
	ds_write_b16 v8, v12 offset:1728
	v_cndmask_b32_e64 v14, 0, 1.0, vcc
	s_waitcnt lgkmcnt(15)
	v_pk_fma_f32 v[16:17], v[86:87], v[98:99], v[14:15] neg_lo:[1,0,0] neg_hi:[1,0,0]
	v_pk_fma_f32 v[22:23], v[88:89], v[100:101], 0 neg_lo:[1,0,0] neg_hi:[1,0,0]
	s_waitcnt lgkmcnt(15)
	v_pk_fma_f32 v[16:17], v[190:191], v[102:103], v[16:17] neg_lo:[1,0,0] neg_hi:[1,0,0]
	v_pk_fma_f32 v[22:23], v[192:193], v[104:105], v[22:23] neg_lo:[1,0,0] neg_hi:[1,0,0]
	s_waitcnt lgkmcnt(15)
	v_pk_fma_f32 v[16:17], v[210:211], v[106:107], v[16:17] neg_lo:[1,0,0] neg_hi:[1,0,0]
	v_pk_fma_f32 v[22:23], v[212:213], v[108:109], v[22:23] neg_lo:[1,0,0] neg_hi:[1,0,0]
	s_waitcnt lgkmcnt(15)
	v_pk_fma_f32 v[16:17], v[90:91], v[110:111], v[16:17] neg_lo:[1,0,0] neg_hi:[1,0,0]
	v_pk_fma_f32 v[22:23], v[92:93], v[112:113], v[22:23] neg_lo:[1,0,0] neg_hi:[1,0,0]
	v_cmp_eq_u32_e32 vcc, 14, v0
	v_pk_add_f32 v[18:19], v[16:17], v[22:23]
	v_add_f32_e32 v111, v18, v19
	v_cvt_pk_bf16_f32 v12, v111, v111
	ds_write_b16 v8, v12 offset:1872
	v_cndmask_b32_e64 v14, 0, 1.0, vcc
	s_waitcnt lgkmcnt(14)
	v_pk_fma_f32 v[16:17], v[26:27], v[98:99], v[14:15] neg_lo:[1,0,0] neg_hi:[1,0,0]
	v_pk_fma_f32 v[22:23], v[28:29], v[100:101], 0 neg_lo:[1,0,0] neg_hi:[1,0,0]
	s_waitcnt lgkmcnt(13)
	v_pk_fma_f32 v[16:17], v[34:35], v[102:103], v[16:17] neg_lo:[1,0,0] neg_hi:[1,0,0]
	v_pk_fma_f32 v[22:23], v[36:37], v[104:105], v[22:23] neg_lo:[1,0,0] neg_hi:[1,0,0]
	s_waitcnt lgkmcnt(12)
	v_pk_fma_f32 v[16:17], v[38:39], v[106:107], v[16:17] neg_lo:[1,0,0] neg_hi:[1,0,0]
	v_pk_fma_f32 v[22:23], v[40:41], v[108:109], v[22:23] neg_lo:[1,0,0] neg_hi:[1,0,0]
	s_waitcnt lgkmcnt(10)
	v_pk_fma_f32 v[16:17], v[42:43], v[110:111], v[16:17] neg_lo:[1,0,0] neg_hi:[1,0,0]
	v_pk_fma_f32 v[22:23], v[44:45], v[112:113], v[22:23] neg_lo:[1,0,0] neg_hi:[1,0,0]
	v_cmp_eq_u32_e32 vcc, 15, v0
	v_pk_add_f32 v[18:19], v[16:17], v[22:23]
	v_add_f32_e32 v112, v18, v19
	v_cvt_pk_bf16_f32 v12, v112, v112
	ds_write_b16 v8, v12 offset:2016
	v_cndmask_b32_e64 v14, 0, 1.0, vcc
	s_waitcnt lgkmcnt(10)
	v_pk_fma_f32 v[16:17], v[46:47], v[98:99], v[14:15] neg_lo:[1,0,0] neg_hi:[1,0,0]
	v_pk_fma_f32 v[22:23], v[48:49], v[100:101], 0 neg_lo:[1,0,0] neg_hi:[1,0,0]
	s_waitcnt lgkmcnt(9)
	v_pk_fma_f32 v[16:17], v[50:51], v[102:103], v[16:17] neg_lo:[1,0,0] neg_hi:[1,0,0]
	v_pk_fma_f32 v[22:23], v[52:53], v[104:105], v[22:23] neg_lo:[1,0,0] neg_hi:[1,0,0]
	s_waitcnt lgkmcnt(7)
	v_pk_fma_f32 v[16:17], v[54:55], v[106:107], v[16:17] neg_lo:[1,0,0] neg_hi:[1,0,0]
	v_pk_fma_f32 v[22:23], v[56:57], v[108:109], v[22:23] neg_lo:[1,0,0] neg_hi:[1,0,0]
	s_waitcnt lgkmcnt(6)
	v_pk_fma_f32 v[16:17], v[58:59], v[110:111], v[16:17] neg_lo:[1,0,0] neg_hi:[1,0,0]
	v_pk_fma_f32 v[22:23], v[60:61], v[112:113], v[22:23] neg_lo:[1,0,0] neg_hi:[1,0,0]
	v_pk_add_f32 v[18:19], v[16:17], v[22:23]
	v_add_f32_e32 v113, v18, v19
	v_cvt_pk_bf16_f32 v12, v113, v113
	ds_write_b16 v8, v12 offset:2160
	ds_write_b128 v6, v[98:101] offset:17408
	ds_write_b128 v6, v[102:105] offset:17424
	ds_write_b128 v6, v[106:109] offset:17440
	ds_write_b128 v6, v[110:113] offset:17456
	s_mov_b32 exec_lo, 0xffff0000
	ds_write_b32 v7, v98 offset:17408
	ds_write_b32 v7, v99 offset:17664
	ds_write_b32 v7, v100 offset:17920
	ds_write_b32 v7, v101 offset:18176
	ds_write_b32 v7, v102 offset:18432
	ds_write_b32 v7, v103 offset:18688
	ds_write_b32 v7, v104 offset:18944
	ds_write_b32 v7, v105 offset:19200
	ds_write_b32 v7, v106 offset:19456
	ds_write_b32 v7, v107 offset:19712
	ds_write_b32 v7, v108 offset:19968
	ds_write_b32 v7, v109 offset:20224
	ds_write_b32 v7, v110 offset:20480
	ds_write_b32 v7, v111 offset:20736
	ds_write_b32 v7, v112 offset:20992
	ds_write_b32 v7, v113 offset:21248
	s_mov_b32 exec_lo, -1
	s_nop 3
	ds_read_b128 v[122:125], v2 offset:21504
	ds_read_b128 v[126:129], v2 offset:17408
	ds_read_b128 v[130:133], v2 offset:29824
	ds_read_b128 v[134:137], v2 offset:25728
	s_waitcnt lgkmcnt(2)
	v_mfma_f32_16x16x4_f32 v[114:117], v122, v126, 0
	s_waitcnt lgkmcnt(0)
	v_mfma_f32_16x16x4_f32 v[118:121], v130, v134, 0
	v_mfma_f32_16x16x4_f32 v[114:117], v123, v127, v[114:117]
	v_mfma_f32_16x16x4_f32 v[118:121], v131, v135, v[118:121]
	v_mfma_f32_16x16x4_f32 v[114:117], v124, v128, v[114:117]
	v_mfma_f32_16x16x4_f32 v[118:121], v132, v136, v[118:121]
	v_mfma_f32_16x16x4_f32 v[114:117], v125, v129, v[114:117]
	v_mfma_f32_16x16x4_f32 v[118:121], v133, v137, v[118:121]
	s_nop 7
	s_nop 3
	ds_write_b128 v2, v[114:117] offset:21632
	ds_write_b128 v2, v[118:121] offset:21696
	ds_read_b128 v[122:125], v2 offset:17472
	ds_read_b128 v[126:129], v2 offset:21632
	ds_read_b128 v[130:133], v2 offset:17600
	ds_read_b128 v[134:137], v2 offset:21696
	s_waitcnt lgkmcnt(2)
	v_mfma_f32_16x16x4_f32 v[114:117], v122, v126, 0
	s_waitcnt lgkmcnt(0)
	v_mfma_f32_16x16x4_f32 v[118:121], v130, v134, 0
	v_mfma_f32_16x16x4_f32 v[114:117], v123, v127, v[114:117]
	v_mfma_f32_16x16x4_f32 v[118:121], v131, v135, v[118:121]
	v_mfma_f32_16x16x4_f32 v[114:117], v124, v128, v[114:117]
	v_mfma_f32_16x16x4_f32 v[118:121], v132, v136, v[118:121]
	v_mfma_f32_16x16x4_f32 v[114:117], v125, v129, v[114:117]
	v_mfma_f32_16x16x4_f32 v[118:121], v133, v137, v[118:121]
	s_nop 7
	s_nop 3
	v_xor_b32_e32 v114, 0x80000000, v114
	v_xor_b32_e32 v115, 0x80000000, v115
	v_xor_b32_e32 v116, 0x80000000, v116
	v_xor_b32_e32 v117, 0x80000000, v117
	v_xor_b32_e32 v118, 0x80000000, v118
	v_xor_b32_e32 v119, 0x80000000, v119
	v_xor_b32_e32 v120, 0x80000000, v120
	v_xor_b32_e32 v121, 0x80000000, v121
	ds_write_b128 v2, v[114:117] offset:21504
	ds_write_b32 v3, v118 offset:29824
	ds_write_b32 v3, v119 offset:30080
	ds_write_b32 v3, v120 offset:30336
	ds_write_b32 v3, v121 offset:30592
	v_cvt_pk_bf16_f32 v10, v114, v115
	v_cvt_pk_bf16_f32 v11, v116, v117
	ds_write_b16 v4, v10 offset:2304
	ds_write_b16_d16_hi v4, v10 offset:2448
	ds_write_b16 v4, v11 offset:2592
	ds_write_b16_d16_hi v4, v11 offset:2736
	v_cvt_pk_bf16_f32 v10, v118, v119
	v_cvt_pk_bf16_f32 v11, v120, v121
	ds_write_b16 v4, v10 offset:6976
	ds_write_b16_d16_hi v4, v10 offset:7120
	ds_write_b16 v4, v11 offset:7264
	ds_write_b16_d16_hi v4, v11 offset:7408
.Linv_A:
	s_waitcnt lgkmcnt(0)
	s_barrier
	s_cmp_lt_u32 s9, 2
	s_cbranch_scc0 .Linv_4hi
	s_cmp_eq_u32 s9, 0
	s_cbranch_scc0 .Linv_41
.Linv_40:
	ds_read_b128 v[122:125], v2 offset:25600
	ds_read_b128 v[126:129], v2 offset:17408
	ds_read_b128 v[130:133], v2 offset:25664
	ds_read_b128 v[134:137], v2 offset:21504
	s_waitcnt lgkmcnt(2)
	v_mfma_f32_16x16x4_f32 v[114:117], v122, v126, 0
	s_waitcnt lgkmcnt(0)
	v_mfma_f32_16x16x4_f32 v[118:121], v130, v134, 0
	v_mfma_f32_16x16x4_f32 v[114:117], v123, v127, v[114:117]
	v_mfma_f32_16x16x4_f32 v[118:121], v131, v135, v[118:121]
	v_mfma_f32_16x16x4_f32 v[114:117], v124, v128, v[114:117]
	v_mfma_f32_16x16x4_f32 v[118:121], v132, v136, v[118:121]
	v_mfma_f32_16x16x4_f32 v[114:117], v125, v129, v[114:117]
	v_mfma_f32_16x16x4_f32 v[118:121], v133, v137, v[118:121]
	s_nop 7
	s_nop 3
	v_pk_add_f32 v[114:115], v[114:115], v[118:119]
	v_pk_add_f32 v[116:117], v[116:117], v[120:121]
	ds_write_b128 v2, v[114:117] offset:21632
	s_branch .Linv_B
.Linv_41:
	ds_read_b128 v[122:125], v2 offset:25664
	ds_read_b128 v[126:129], v2 offset:21568
	s_waitcnt lgkmcnt(0)
	v_mfma_f32_16x16x4_f32 v[114:117], v122, v126, 0
	v_mfma_f32_16x16x4_f32 v[114:117], v123, v127, v[114:117]
	v_mfma_f32_16x16x4_f32 v[114:117], v124, v128, v[114:117]
	v_mfma_f32_16x16x4_f32 v[114:117], v125, v129, v[114:117]
	s_nop 7
	s_nop 3
	ds_write_b128 v2, v[114:117] offset:21696
	s_branch .Linv_B
.Linv_4hi:
	s_cmp_eq_u32 s9, 2
	s_cbranch_scc0 .Linv_43
.Linv_42:
	ds_read_b128 v[122:125], v2 offset:29696
	ds_read_b128 v[126:129], v2 offset:17408
	ds_read_b128 v[130:133], v2 offset:29760
	ds_read_b128 v[134:137], v2 offset:21504
	s_waitcnt lgkmcnt(2)
	v_mfma_f32_16x16x4_f32 v[114:117], v122, v126, 0
	s_waitcnt lgkmcnt(0)
	v_mfma_f32_16x16x4_f32 v[118:121], v130, v134, 0
	v_mfma_f32_16x16x4_f32 v[114:117], v123, v127, v[114:117]
	v_mfma_f32_16x16x4_f32 v[118:121], v131, v135, v[118:121]
	v_mfma_f32_16x16x4_f32 v[114:117], v124, v128, v[114:117]
	v_mfma_f32_16x16x4_f32 v[118:121], v132, v136, v[118:121]
	v_mfma_f32_16x16x4_f32 v[114:117], v125, v129, v[114:117]
	v_mfma_f32_16x16x4_f32 v[118:121], v133, v137, v[118:121]
	s_nop 7
	s_nop 3
	v_pk_add_f32 v[114:115], v[114:115], v[118:119]
	v_pk_add_f32 v[116:117], v[116:117], v[120:121]
	ds_write_b128 v2, v[114:117] offset:25792
	s_branch .Linv_B
.Linv_43:
	ds_read_b128 v[122:125], v2 offset:29760
	ds_read_b128 v[126:129], v2 offset:21568
	s_waitcnt lgkmcnt(0)
	v_mfma_f32_16x16x4_f32 v[114:117], v122, v126, 0
	v_mfma_f32_16x16x4_f32 v[114:117], v123, v127, v[114:117]
	v_mfma_f32_16x16x4_f32 v[114:117], v124, v128, v[114:117]
	v_mfma_f32_16x16x4_f32 v[114:117], v125, v129, v[114:117]
	s_nop 7
	s_nop 3
	ds_write_b128 v2, v[114:117] offset:17472

.Linv_50:
	ds_read_b128 v[122:125], v2 offset:17536
	ds_read_b128 v[126:129], v2 offset:21632
	s_waitcnt lgkmcnt(0)
	v_mfma_f32_16x16x4_f32 v[114:117], v122, v126, 0
	v_mfma_f32_16x16x4_f32 v[114:117], v123, v127, v[114:117]
	v_mfma_f32_16x16x4_f32 v[114:117], v124, v128, v[114:117]
	v_mfma_f32_16x16x4_f32 v[114:117], v125, v129, v[114:117]
	s_nop 7
	s_nop 3
	v_xor_b32_e32 v114, 0x80000000, v114
	v_xor_b32_e32 v115, 0x80000000, v115
	v_xor_b32_e32 v116, 0x80000000, v116
	v_xor_b32_e32 v117, 0x80000000, v117
	v_cvt_pk_bf16_f32 v10, v114, v115
	v_cvt_pk_bf16_f32 v11, v116, v117
	ds_write_b16 v4, v10 offset:4608
	ds_write_b16_d16_hi v4, v10 offset:4752
	ds_write_b16 v4, v11 offset:4896
	ds_write_b16_d16_hi v4, v11 offset:5040
	s_branch .Linv_E
.Linv_51:
	ds_read_b128 v[122:125], v2 offset:17536
	ds_read_b128 v[126:129], v2 offset:21696
	s_waitcnt lgkmcnt(0)
	v_mfma_f32_16x16x4_f32 v[114:117], v122, v126, 0
	v_mfma_f32_16x16x4_f32 v[114:117], v123, v127, v[114:117]
	v_mfma_f32_16x16x4_f32 v[114:117], v124, v128, v[114:117]
	v_mfma_f32_16x16x4_f32 v[114:117], v125, v129, v[114:117]
	s_nop 7
	s_nop 3
	v_xor_b32_e32 v114, 0x80000000, v114
	v_xor_b32_e32 v115, 0x80000000, v115
	v_xor_b32_e32 v116, 0x80000000, v116
	v_xor_b32_e32 v117, 0x80000000, v117
	v_cvt_pk_bf16_f32 v10, v114, v115
	v_cvt_pk_bf16_f32 v11, v116, v117
	ds_write_b16 v4, v10 offset:4640
	ds_write_b16_d16_hi v4, v10 offset:4784
	ds_write_b16 v4, v11 offset:4928
	ds_write_b16_d16_hi v4, v11 offset:5072
	s_branch .Linv_E

.Linv_52:
	ds_read_b128 v[122:125], v2 offset:29824
	ds_read_b128 v[126:129], v2 offset:21632
	ds_read_b128 v[130:133], v2 offset:17600
	ds_read_b128 v[134:137], v2 offset:25792
	s_waitcnt lgkmcnt(2)
	v_mfma_f32_16x16x4_f32 v[114:117], v122, v126, 0
	s_waitcnt lgkmcnt(0)
	v_mfma_f32_16x16x4_f32 v[118:121], v130, v134, 0
	v_mfma_f32_16x16x4_f32 v[114:117], v123, v127, v[114:117]
	v_mfma_f32_16x16x4_f32 v[118:121], v131, v135, v[118:121]
	v_mfma_f32_16x16x4_f32 v[114:117], v124, v128, v[114:117]
	v_mfma_f32_16x16x4_f32 v[118:121], v132, v136, v[118:121]
	v_mfma_f32_16x16x4_f32 v[114:117], v125, v129, v[114:117]
	v_mfma_f32_16x16x4_f32 v[118:121], v133, v137, v[118:121]
	s_nop 7
	s_nop 3
	v_pk_add_f32 v[114:115], v[114:115], v[118:119]
	v_pk_add_f32 v[116:117], v[116:117], v[120:121]
	v_xor_b32_e32 v114, 0x80000000, v114
	v_xor_b32_e32 v115, 0x80000000, v115
	v_xor_b32_e32 v116, 0x80000000, v116
	v_xor_b32_e32 v117, 0x80000000, v117
	v_cvt_pk_bf16_f32 v10, v114, v115
	v_cvt_pk_bf16_f32 v11, v116, v117
	ds_write_b16 v4, v10 offset:6912
	ds_write_b16_d16_hi v4, v10 offset:7056
	ds_write_b16 v4, v11 offset:7200
	ds_write_b16_d16_hi v4, v11 offset:7344
	s_branch .Linv_E
.Linv_53:
	ds_read_b128 v[122:125], v2 offset:29824
	ds_read_b128 v[126:129], v2 offset:21696
	ds_read_b128 v[130:133], v2 offset:17600
	ds_read_b128 v[134:137], v2 offset:17472
	s_waitcnt lgkmcnt(2)
	v_mfma_f32_16x16x4_f32 v[114:117], v122, v126, 0
	s_waitcnt lgkmcnt(0)
	v_mfma_f32_16x16x4_f32 v[118:121], v130, v134, 0
	v_mfma_f32_16x16x4_f32 v[114:117], v123, v127, v[114:117]
	v_mfma_f32_16x16x4_f32 v[118:121], v131, v135, v[118:121]
	v_mfma_f32_16x16x4_f32 v[114:117], v124, v128, v[114:117]
	v_mfma_f32_16x16x4_f32 v[118:121], v132, v136, v[118:121]
	v_mfma_f32_16x16x4_f32 v[114:117], v125, v129, v[114:117]
	v_mfma_f32_16x16x4_f32 v[118:121], v133, v137, v[118:121]
	s_nop 7
	s_nop 3
	v_pk_add_f32 v[114:115], v[114:115], v[118:119]
	v_pk_add_f32 v[116:117], v[116:117], v[120:121]
	v_xor_b32_e32 v114, 0x80000000, v114
	v_xor_b32_e32 v115, 0x80000000, v115
	v_xor_b32_e32 v116, 0x80000000, v116
	v_xor_b32_e32 v117, 0x80000000, v117
	v_cvt_pk_bf16_f32 v10, v114, v115
	v_cvt_pk_bf16_f32 v11, v116, v117
	ds_write_b16 v4, v10 offset:6944
	ds_write_b16_d16_hi v4, v10 offset:7088
	ds_write_b16 v4, v11 offset:7232
	ds_write_b16_d16_hi v4, v11 offset:7376
.Linv_E:
.LBB0_227:
	v_mul_u32_u24_e32 v0, 0x90, v151
	v_lshrrev_b32_e32 v33, 3, v151
	v_add3_u32 v48, s19, v0, v24
	v_or_b32_e32 v0, s26, v151
	v_mov_b32_e32 v49, s19
	v_mad_u32_u24 v0, v0, s13, v49
	v_bitop3_b32 v1, v33, v32, s11 bitop3:0x36
	v_lshl_add_u32 v60, v1, 4, v0
	s_waitcnt lgkmcnt(0)
	s_barrier
	ds_read_b128 v[34:37], v60 offset:34816
	v_add_u32_e32 v50, 4, v32
	v_bitop3_b32 v1, v33, v50, s11 bitop3:0x36
	v_lshl_add_u32 v61, v1, 4, v0
	ds_read_b128 v[38:41], v61 offset:34816
	ds_read_b128 v[28:31], v48
	ds_read_b128 v[24:27], v48 offset:64
	s_waitcnt lgkmcnt(1)
	v_mfma_f32_16x16x32_bf16 v[0:3], v[34:37], v[28:31], 0
	s_add_u32 s8, s55, s48
	s_addc_u32 s9, s3, s49
	v_lshlrev_b64 v[58:59], 1, v[20:21]
	s_waitcnt lgkmcnt(0)
	v_mfma_f32_16x16x32_bf16 v[0:3], v[38:41], v[24:27], v[0:3]
	v_lshl_add_u64 v[54:55], s[8:9], 0, v[58:59]
	s_lshl_b32 s76, s26, 1
	v_lshl_add_u64 v[46:47], v[54:55], 0, s[76:77]
	v_lshlrev_b32_e32 v84, 8, v151
	v_or_b32_e32 v44, 0x1000, v84
	s_nop 2
	v_cvt_pk_bf16_f32 v0, v0, v1
	v_cvt_pk_bf16_f32 v1, v2, v3
	v_lshl_add_u64 v[2:3], v[46:47], 0, v[84:85]
	global_store_dwordx2 v[2:3], v[0:1], off
	ds_read_b128 v[20:23], v48 offset:2304
	ds_read_b128 v[16:19], v48 offset:2368
	s_waitcnt lgkmcnt(1)
	v_mfma_f32_16x16x32_bf16 v[0:3], v[34:37], v[20:23], 0
	v_mov_b32_e32 v45, v85
	v_or_b32_e32 v42, 0x2000, v84
	v_mov_b32_e32 v43, v85
	s_waitcnt lgkmcnt(0)
	v_mfma_f32_16x16x32_bf16 v[0:3], v[38:41], v[16:19], v[0:3]
	v_bitop3_b32 v32, v33, v32, s27 bitop3:0x36
	v_bitop3_b32 v33, v33, v50, s27 bitop3:0x36
	s_lshl_b32 s42, s4, 1
	s_mov_b32 s43, s77
	s_add_u32 s8, s0, s48
	s_nop 2
	v_cvt_pk_bf16_f32 v0, v0, v1
	v_cvt_pk_bf16_f32 v1, v2, v3
	v_lshl_add_u64 v[2:3], v[46:47], 0, v[44:45]
	global_store_dwordx2 v[2:3], v[0:1], off
	ds_read_b128 v[12:15], v48 offset:4608
	ds_read_b128 v[8:11], v48 offset:4672
	s_waitcnt lgkmcnt(1)
	v_mfma_f32_16x16x32_bf16 v[0:3], v[34:37], v[12:15], 0
	s_addc_u32 s9, s1, s49
	s_addk_i32 s72, 8
	s_addk_i32 s84, 0x40
	s_waitcnt lgkmcnt(0)
	v_mfma_f32_16x16x32_bf16 v[0:3], v[38:41], v[8:11], v[0:3]
	s_addk_i32 s85, 0x80
	s_cmpk_lg_i32 s85, 0x280
	s_nop 5
	v_cvt_pk_bf16_f32 v0, v0, v1
	v_cvt_pk_bf16_f32 v1, v2, v3
	v_lshl_add_u64 v[2:3], v[46:47], 0, v[42:43]
	global_store_dwordx2 v[2:3], v[0:1], off
	ds_read_b128 v[4:7], v48 offset:6912
	ds_read_b128 v[0:3], v48 offset:6976
	s_waitcnt lgkmcnt(1)
	v_mfma_f32_16x16x32_bf16 v[34:37], v[34:37], v[4:7], 0
	s_waitcnt lgkmcnt(0)
	v_mfma_f32_16x16x32_bf16 v[34:37], v[38:41], v[0:3], v[34:37]
	v_or_b32_e32 v40, 0x3000, v84
	v_mov_b32_e32 v41, v85
	s_nop 5
	v_cvt_pk_bf16_f32 v34, v34, v35
	v_cvt_pk_bf16_f32 v35, v36, v37
	v_lshl_add_u64 v[36:37], v[46:47], 0, v[40:41]
	global_store_dwordx2 v[36:37], v[34:35], off
	v_or_b32_e32 v34, s4, v151
	v_mad_u32_u24 v34, v34, s13, v49
	v_lshl_add_u32 v32, v32, 4, v34
	ds_read_b128 v[46:49], v32 offset:34816
	v_lshl_add_u32 v36, v33, 4, v34
	ds_read_b128 v[50:53], v36 offset:34816
	v_lshl_add_u64 v[34:35], v[54:55], 0, s[42:43]
	s_waitcnt lgkmcnt(1)
	v_mfma_f32_16x16x32_bf16 v[54:57], v[46:49], v[28:31], 0
	s_waitcnt lgkmcnt(0)
	v_mfma_f32_16x16x32_bf16 v[54:57], v[50:53], v[24:27], v[54:57]
	s_nop 7
	v_cvt_pk_bf16_f32 v38, v54, v55
	v_cvt_pk_bf16_f32 v39, v56, v57
	v_lshl_add_u64 v[54:55], v[34:35], 0, v[84:85]
	global_store_dwordx2 v[54:55], v[38:39], off
	v_mfma_f32_16x16x32_bf16 v[54:57], v[46:49], v[20:23], 0
	v_mfma_f32_16x16x32_bf16 v[54:57], v[50:53], v[16:19], v[54:57]
	s_nop 7
	v_cvt_pk_bf16_f32 v38, v54, v55
	v_cvt_pk_bf16_f32 v39, v56, v57
	v_lshl_add_u64 v[54:55], v[34:35], 0, v[44:45]
	global_store_dwordx2 v[54:55], v[38:39], off
	v_mfma_f32_16x16x32_bf16 v[54:57], v[46:49], v[12:15], 0
	v_mfma_f32_16x16x32_bf16 v[46:49], v[46:49], v[4:7], 0
	v_mfma_f32_16x16x32_bf16 v[54:57], v[50:53], v[8:11], v[54:57]
	v_mfma_f32_16x16x32_bf16 v[46:49], v[50:53], v[0:3], v[46:49]
	s_nop 6
	v_cvt_pk_bf16_f32 v38, v54, v55
	v_cvt_pk_bf16_f32 v39, v56, v57
	v_lshl_add_u64 v[54:55], v[34:35], 0, v[42:43]
	global_store_dwordx2 v[54:55], v[38:39], off
	v_cvt_pk_bf16_f32 v38, v46, v47
	v_cvt_pk_bf16_f32 v39, v48, v49
	v_lshl_add_u64 v[34:35], v[34:35], 0, v[40:41]
	global_store_dwordx2 v[34:35], v[38:39], off
	ds_read_b128 v[48:51], v60 offset:53248
	ds_read_b128 v[52:55], v61 offset:53248
	v_lshl_add_u64 v[46:47], s[8:9], 0, v[58:59]
	s_waitcnt lgkmcnt(1)
	v_mfma_f32_16x16x32_bf16 v[56:59], v[48:51], v[28:31], 0
	v_lshl_add_u64 v[34:35], v[46:47], 0, s[76:77]
	v_lshl_add_u64 v[46:47], v[46:47], 0, s[42:43]
	s_waitcnt lgkmcnt(0)
	v_mfma_f32_16x16x32_bf16 v[56:59], v[52:55], v[24:27], v[56:59]
	s_nop 7
	v_cvt_pk_bf16_f32 v38, v56, v57
	v_cvt_pk_bf16_f32 v39, v58, v59
	v_lshl_add_u64 v[56:57], v[34:35], 0, v[84:85]
	global_store_dwordx2 v[56:57], v[38:39], off
	v_mfma_f32_16x16x32_bf16 v[56:59], v[48:51], v[20:23], 0
	v_mfma_f32_16x16x32_bf16 v[56:59], v[52:55], v[16:19], v[56:59]
	s_nop 7
	v_cvt_pk_bf16_f32 v38, v56, v57
	v_cvt_pk_bf16_f32 v39, v58, v59
	v_lshl_add_u64 v[56:57], v[34:35], 0, v[44:45]
	global_store_dwordx2 v[56:57], v[38:39], off
	v_mfma_f32_16x16x32_bf16 v[56:59], v[48:51], v[12:15], 0
	v_mfma_f32_16x16x32_bf16 v[48:51], v[48:51], v[4:7], 0
	v_mfma_f32_16x16x32_bf16 v[56:59], v[52:55], v[8:11], v[56:59]
	v_mfma_f32_16x16x32_bf16 v[48:51], v[52:55], v[0:3], v[48:51]
	s_nop 6
	v_cvt_pk_bf16_f32 v38, v56, v57
	v_cvt_pk_bf16_f32 v39, v58, v59
	v_lshl_add_u64 v[56:57], v[34:35], 0, v[42:43]
	global_store_dwordx2 v[56:57], v[38:39], off
	v_cvt_pk_bf16_f32 v38, v48, v49
	v_cvt_pk_bf16_f32 v39, v50, v51
	v_lshl_add_u64 v[34:35], v[34:35], 0, v[40:41]
	global_store_dwordx2 v[34:35], v[38:39], off
	ds_read_b128 v[32:35], v32 offset:53248
	ds_read_b128 v[36:39], v36 offset:53248
	s_waitcnt lgkmcnt(1)
	v_mfma_f32_16x16x32_bf16 v[28:31], v[32:35], v[28:31], 0
	v_mfma_f32_16x16x32_bf16 v[20:23], v[32:35], v[20:23], 0
	v_mfma_f32_16x16x32_bf16 v[12:15], v[32:35], v[12:15], 0
	v_mfma_f32_16x16x32_bf16 v[4:7], v[32:35], v[4:7], 0
	s_waitcnt lgkmcnt(0)
	v_mfma_f32_16x16x32_bf16 v[24:27], v[36:39], v[24:27], v[28:31]
	v_mfma_f32_16x16x32_bf16 v[16:19], v[36:39], v[16:19], v[20:23]
	v_mfma_f32_16x16x32_bf16 v[8:11], v[36:39], v[8:11], v[12:15]
	s_nop 5
	v_cvt_pk_bf16_f32 v24, v24, v25
	v_cvt_pk_bf16_f32 v25, v26, v27
	v_lshl_add_u64 v[26:27], v[46:47], 0, v[84:85]
	v_mfma_f32_16x16x32_bf16 v[0:3], v[36:39], v[0:3], v[4:7]
	v_cvt_pk_bf16_f32 v16, v16, v17
	v_cvt_pk_bf16_f32 v17, v18, v19
	v_lshl_add_u64 v[18:19], v[46:47], 0, v[44:45]
	v_cvt_pk_bf16_f32 v8, v8, v9
	v_cvt_pk_bf16_f32 v9, v10, v11
	v_lshl_add_u64 v[10:11], v[46:47], 0, v[42:43]
	s_nop 1
	v_cvt_pk_bf16_f32 v0, v0, v1
	v_cvt_pk_bf16_f32 v1, v2, v3
	v_lshl_add_u64 v[2:3], v[46:47], 0, v[40:41]
	global_store_dwordx2 v[26:27], v[24:25], off
	global_store_dwordx2 v[18:19], v[16:17], off
	global_store_dwordx2 v[10:11], v[8:9], off
	global_store_dwordx2 v[2:3], v[0:1], off
	s_barrier
	s_cbranch_scc0 .LBB0_308

.LBB0_304:
	s_cmpk_eq_i32 s85, 0x200
	s_cselect_b64 s[8:9], -1, 0
	s_or_b64 s[8:9], s[30:31], s[8:9]
	s_and_b64 vcc, exec, s[8:9]
	s_waitcnt lgkmcnt(0)
	s_barrier
	s_cbranch_vccnz .LBB0_226
	s_and_b32 s8, s84, 0xfffff800
	s_lshl_b32 s9, s84, 3
	s_and_b32 s9, s9, 0x7c0
	s_or_b32 s8, s8, s9
	v_mbcnt_lo_u32_b32 v0, -1, 0
	v_mbcnt_hi_u32_b32 v0, -1, v0
	s_mov_b32 s42, 0xbfb8aa3b
	v_add_u32_e32 v2, s8, v0
	v_ashrrev_i32_e32 v3, 31, v2
	v_readlane_b32 s8, v241, 17
	v_lshlrev_b64 v[2:3], 6, v[2:3]
	v_readlane_b32 s9, v241, 18
	s_mov_b32 s43, 0x42ce8ed0
	s_mov_b32 s44, 0xc2b17218
	v_lshl_add_u64 v[2:3], s[8:9], 0, v[2:3]
	global_load_dword v1, v[2:3], off
	s_nop 0
	global_load_dword v2, v[2:3], off offset:32
	v_readlane_b32 s8, v241, 19
	v_readlane_b32 s9, v241, 20
	s_waitcnt vmcnt(1)
	v_mul_f32_e32 v3, 0xbfb8aa3b, v1
	v_fma_f32 v4, v1, s42, -v3
	v_rndne_f32_e32 v5, v3
	v_fmac_f32_e32 v4, 0xb2a5705f, v1
	v_sub_f32_e32 v3, v3, v5
	v_add_f32_e32 v3, v3, v4
	v_exp_f32_e32 v3, v3
	v_cvt_i32_f32_e32 v4, v5
	v_cmp_nlt_f32_e32 vcc, s43, v1
	v_ldexp_f32 v3, v3, v4
	s_nop 0
	v_cndmask_b32_e32 v3, 0, v3, vcc
	v_cmp_ngt_f32_e32 vcc, s44, v1
	s_nop 1
	v_cndmask_b32_e32 v1, v150, v3, vcc
	global_load_dword v3, v85, s[8:9]
	s_mov_b32 s8, 0xb2a5705f
	v_add_f32_e32 v1, 1.0, v1
	s_waitcnt vmcnt(0)
	v_add_f32_e32 v2, v2, v3
	v_mul_f32_e64 v3, |v2|, s42
	v_fma_f32 v5, |v2|, s42, -v3
	v_rndne_f32_e32 v6, v3
	v_fma_f32 v5, |v2|, s8, v5
	v_sub_f32_e32 v3, v3, v6
	v_add_f32_e32 v3, v3, v5
	v_exp_f32_e32 v3, v3
	v_cvt_i32_f32_e32 v5, v6
	v_cmp_ngt_f32_e64 vcc, |v2|, s43
	v_max_f32_e32 v4, 0, v2
	s_mov_b32 s8, 0x3f2aaaab
	v_ldexp_f32 v3, v3, v5
	v_cndmask_b32_e32 v3, 0, v3, vcc
	v_cmp_nlt_f32_e64 vcc, |v2|, s44
	s_nop 1
	v_cndmask_b32_e32 v5, v150, v3, vcc
	v_add_f32_e32 v6, 1.0, v5
	v_add_f32_e32 v2, -1.0, v6
	v_sub_f32_e32 v3, v2, v6
	v_add_f32_e32 v3, 1.0, v3
	v_sub_f32_e32 v2, v5, v2
	v_add_f32_e32 v7, v2, v3
	v_frexp_mant_f32_e32 v2, v6
	v_cmp_gt_f32_e32 vcc, s8, v2
	v_cvt_f64_f32_e32 v[2:3], v6
	v_frexp_exp_i32_f64_e32 v2, v[2:3]
	v_subbrev_co_u32_e32 v2, vcc, 0, v2, vcc
	v_sub_u32_e32 v3, 0, v2
	v_ldexp_f32 v6, v6, v3
	v_ldexp_f32 v3, v7, v3
	v_add_f32_e32 v7, -1.0, v6
	v_add_f32_e32 v8, 1.0, v7
	v_sub_f32_e32 v8, v6, v8
	v_add_f32_e32 v8, v3, v8
	v_add_f32_e32 v9, v7, v8
	v_sub_f32_e32 v7, v7, v9
	v_add_f32_e32 v7, v8, v7
	v_add_f32_e32 v8, 1.0, v6
	v_add_f32_e32 v10, -1.0, v8
	v_sub_f32_e32 v6, v6, v10
	v_add_f32_e32 v3, v3, v6
	v_add_f32_e32 v6, v8, v3
	v_sub_f32_e32 v8, v8, v6
	v_add_f32_e32 v3, v3, v8
	v_rcp_f32_e32 v8, v6
	v_cvt_f32_i32_e32 v2, v2
	s_mov_b32 s8, 0x3f317218
	v_mul_f32_e32 v10, v9, v8
	v_mul_f32_e32 v11, v6, v10
	v_fma_f32 v12, v10, v6, -v11
	v_fmac_f32_e32 v12, v10, v3
	v_add_f32_e32 v13, v11, v12
	v_sub_f32_e32 v14, v9, v13
	v_sub_f32_e32 v9, v9, v14
	v_sub_f32_e32 v11, v13, v11
	v_sub_f32_e32 v9, v9, v13
	v_add_f32_e32 v7, v7, v9
	v_sub_f32_e32 v9, v11, v12
	v_add_f32_e32 v7, v9, v7
	v_add_f32_e32 v9, v14, v7
	v_mul_f32_e32 v11, v8, v9
	v_mul_f32_e32 v12, v6, v11
	v_fma_f32 v6, v11, v6, -v12
	v_fmac_f32_e32 v6, v11, v3
	v_sub_f32_e32 v3, v14, v9
	v_add_f32_e32 v3, v7, v3
	v_add_f32_e32 v7, v12, v6
	v_sub_f32_e32 v13, v9, v7
	v_sub_f32_e32 v9, v9, v13
	v_sub_f32_e32 v12, v7, v12
	v_sub_f32_e32 v7, v9, v7
	v_add_f32_e32 v3, v3, v7
	v_sub_f32_e32 v6, v12, v6
	v_add_f32_e32 v3, v6, v3
	v_add_f32_e32 v6, v10, v11
	v_add_f32_e32 v3, v13, v3
	v_sub_f32_e32 v7, v6, v10
	v_mul_f32_e32 v3, v8, v3
	v_sub_f32_e32 v7, v11, v7
	v_add_f32_e32 v3, v7, v3
	v_mul_f32_e32 v10, 0x3f317218, v2
	v_add_f32_e32 v7, v6, v3
	v_fma_f32 v11, v2, s8, -v10
	v_mul_f32_e32 v8, v7, v7
	v_fmac_f32_e32 v11, 0xb102e308, v2
	v_sub_f32_e32 v2, v7, v6
	v_fmamk_f32 v9, v8, 0x3e9b6dac, v147
	v_sub_f32_e32 v2, v3, v2
	v_add_f32_e32 v3, v10, v11
	v_fmaak_f32 v9, v8, v9, 0x3f2aaada
	v_sub_f32_e32 v6, v3, v10
	v_ldexp_f32 v10, v7, 1
	v_mul_f32_e32 v7, v7, v8
	v_mul_f32_e32 v7, v7, v9
	v_add_f32_e32 v8, v10, v7
	v_sub_f32_e32 v9, v8, v10
	v_ldexp_f32 v2, v2, 1
	v_sub_f32_e32 v7, v7, v9
	v_add_f32_e32 v2, v2, v7
	v_add_f32_e32 v7, v8, v2
	v_sub_f32_e32 v8, v7, v8
	v_sub_f32_e32 v2, v2, v8
	v_add_f32_e32 v8, v3, v7
	v_sub_f32_e32 v9, v8, v3
	v_sub_f32_e32 v10, v8, v9
	v_sub_f32_e32 v6, v11, v6
	v_sub_f32_e32 v3, v3, v10
	v_sub_f32_e32 v7, v7, v9
	v_add_f32_e32 v3, v7, v3
	v_add_f32_e32 v7, v6, v2
	v_sub_f32_e32 v9, v7, v6
	v_sub_f32_e32 v10, v7, v9
	v_sub_f32_e32 v6, v6, v10
	v_sub_f32_e32 v2, v2, v9
	v_add_f32_e32 v3, v7, v3
	v_add_f32_e32 v2, v2, v6
	v_add_f32_e32 v6, v8, v3
	v_sub_f32_e32 v7, v6, v8
	v_sub_f32_e32 v3, v3, v7
	v_add_f32_e32 v2, v2, v3
	s_mov_b32 s8, 0x7f800000
	v_add_f32_e32 v2, v6, v2
	v_cmp_neq_f32_e32 vcc, s8, v5
	s_mov_b32 s8, 0x33800000
	s_nop 0
	v_cndmask_b32_e32 v2, v150, v2, vcc
	v_cmp_lt_f32_e64 vcc, |v5|, s8
	v_readlane_b32 s8, v241, 21
	v_readlane_b32 s9, v241, 22
	v_cndmask_b32_e32 v2, v2, v5, vcc
	v_add_f32_e32 v2, v4, v2
	s_nop 2
	global_load_dword v3, v85, s[8:9]
	s_mov_b32 s8, 0x3fb8aa3b
	s_waitcnt vmcnt(0)
	v_mul_f32_e32 v4, 0x3fb8aa3b, v3
	v_fma_f32 v5, v3, s8, -v4
	v_rndne_f32_e32 v6, v4
	v_fmac_f32_e32 v5, 0x32a5705f, v3
	v_sub_f32_e32 v4, v4, v6
	v_add_f32_e32 v4, v4, v5
	v_exp_f32_e32 v4, v4
	v_cvt_i32_f32_e32 v5, v6
	s_mov_b32 s8, 0xc2ce8ed0
	v_cmp_ngt_f32_e32 vcc, s8, v3
	s_mov_b32 s8, 0x42b17218
	v_ldexp_f32 v4, v4, v5
	v_cndmask_b32_e32 v4, 0, v4, vcc
	v_cmp_nlt_f32_e32 vcc, s8, v3
	v_add_u32_e32 v5, -1, v159
	s_nop 0
	v_cndmask_b32_e32 v3, v150, v4, vcc
	v_cmp_lt_i32_e32 vcc, v5, v97
	v_mul_f32_e64 v4, v2, -v3
	s_nop 0
	v_cndmask_b32_e32 v5, v5, v159, vcc
	v_lshlrev_b32_e32 v5, 2, v5
	ds_bpermute_b32 v5, v5, v4
	v_cmp_gt_i32_e32 vcc, 1, v0
	s_waitcnt lgkmcnt(0)
	v_fma_f32 v2, v2, -v3, v5
	v_add_u32_e32 v3, -2, v159
	v_cndmask_b32_e32 v2, v2, v4, vcc
	v_cmp_lt_i32_e32 vcc, v3, v97
	v_div_scale_f32 v4, s[8:9], v1, v1, 1.0
	s_nop 0
	v_cndmask_b32_e32 v3, v3, v159, vcc
	v_lshlrev_b32_e32 v3, 2, v3
	ds_bpermute_b32 v3, v3, v2
	v_cmp_gt_i32_e32 vcc, 2, v0
	v_rcp_f32_e32 v5, v4
	s_and_b32 s8, s85, 0x80
	s_lshl_b32 s8, s8, 2
	s_waitcnt lgkmcnt(0)
	v_add_f32_e32 v3, v2, v3
	v_cndmask_b32_e32 v2, v3, v2, vcc
	v_add_u32_e32 v3, -4, v159
	v_cmp_lt_i32_e32 vcc, v3, v97
	v_fma_f32 v6, -v4, v5, 1.0
	v_fmac_f32_e32 v5, v6, v5
	v_cndmask_b32_e32 v3, v3, v159, vcc
	v_lshlrev_b32_e32 v3, 2, v3
	ds_bpermute_b32 v3, v3, v2
	v_cmp_gt_i32_e32 vcc, 4, v0
	s_add_i32 s8, s18, s8
	s_waitcnt lgkmcnt(0)
	v_add_f32_e32 v3, v2, v3
	v_cndmask_b32_e32 v2, v3, v2, vcc
	v_add_u32_e32 v3, -8, v159
	v_cmp_lt_i32_e32 vcc, v3, v97
	s_nop 1
	v_cndmask_b32_e32 v3, v3, v159, vcc
	v_lshlrev_b32_e32 v3, 2, v3
	ds_bpermute_b32 v3, v3, v2
	v_cmp_gt_i32_e32 vcc, 8, v0
	s_waitcnt lgkmcnt(0)
	v_add_f32_e32 v3, v2, v3
	v_cndmask_b32_e32 v2, v3, v2, vcc
	v_add_u32_e32 v3, -16, v159
	v_cmp_lt_i32_e32 vcc, v3, v97
	s_nop 1
	v_cndmask_b32_e32 v3, v3, v159, vcc
	v_lshlrev_b32_e32 v3, 2, v3
	ds_bpermute_b32 v3, v3, v2
	v_cmp_gt_i32_e32 vcc, 16, v0
	s_waitcnt lgkmcnt(0)
	v_add_f32_e32 v3, v2, v3
	v_cndmask_b32_e32 v3, v3, v2, vcc
	v_subrev_u32_e32 v2, 32, v159
	v_cmp_lt_i32_e32 vcc, v2, v97
	s_nop 1
	v_cndmask_b32_e32 v2, v2, v159, vcc
	v_lshlrev_b32_e32 v2, 2, v2
	ds_bpermute_b32 v2, v2, v3
	v_cmp_gt_i32_e32 vcc, 32, v0
	s_waitcnt lgkmcnt(0)
	v_add_f32_e32 v2, v3, v2
	v_cndmask_b32_e32 v3, v2, v3, vcc
	v_div_scale_f32 v6, vcc, 1.0, v1, 1.0
	v_mul_f32_e32 v7, v6, v5
	v_fma_f32 v8, -v4, v7, v6
	v_fmac_f32_e32 v7, v8, v5
	v_fma_f32 v4, -v4, v7, v6
	v_div_fmas_f32 v4, v4, v5, v7
	v_div_fixup_f32 v1, v4, v1, 1.0
	v_lshl_add_u32 v4, v0, 2, s8
	v_cmp_eq_u32_e32 vcc, 63, v0
	ds_write2st64_b32 v4, v3, v1 offset1:1
	s_and_saveexec_b64 s[8:9], vcc
	s_cbranch_execz .LBB0_225
	v_mul_f32_e32 v0, 0x3fb8aa3b, v2
	v_rndne_f32_e32 v1, v0
	s_mov_b32 s42, 0x3fb8aa3b
	v_sub_f32_e32 v3, v0, v1
	v_fma_f32 v0, v2, s42, -v0
	v_fmac_f32_e32 v0, 0x32a5705f, v2
	v_add_f32_e32 v0, v3, v0
	v_exp_f32_e32 v0, v0
	v_cvt_i32_f32_e32 v1, v1
	s_mov_b32 s43, 0xc2ce8ed0
	s_add_i32 s42, s72, 8
	v_cmp_ngt_f32_e32 vcc, s43, v2
	v_ldexp_f32 v0, v0, v1
	s_mov_b32 s43, 0x42b17218
	v_cndmask_b32_e32 v0, 0, v0, vcc
	v_cmp_nlt_f32_e32 vcc, s43, v2
	s_ashr_i32 s43, s42, 31
	s_lshl_b64 s[42:43], s[42:43], 2
	v_readlane_b32 s44, v241, 7
	v_readlane_b32 s45, v241, 8
	s_add_u32 s42, s44, s42
	v_cndmask_b32_e32 v0, v150, v0, vcc
	s_addc_u32 s43, s45, s43
	global_store_dword v85, v0, s[42:43]
	s_branch .LBB0_225
.LBB0_308:
	s_waitcnt vmcnt(0)
	v_readfirstlane_b32 s4, v194
	s_cmp_gt_u32 s4, 63
	v_readlane_b32 s77, v242, 9
	v_readlane_b32 s78, v241, 13
	v_readlane_b32 s40, v241, 12
	v_readlane_b32 s41, v241, 4
	s_barrier
	s_cbranch_scc1 .LBB0_362
	v_mbcnt_lo_u32_b32 v0, -1, 0
	v_mbcnt_hi_u32_b32 v0, -1, v0
	s_nop 0
	v_cmp_eq_u32_e32 vcc, 0, v0
	s_and_saveexec_b64 s[6:7], vcc
	s_cbranch_execz .LBB0_361
	v_mov_b32_e32 v0, 0x23ff0
	s_waitcnt vmcnt(0) lgkmcnt(0)
	ds_read_b128 v[0:3], v0
	s_waitcnt lgkmcnt(0)
	v_readfirstlane_b32 s8, v2
	s_nop 0
	s_cmp_eq_u32 s8, 0
	s_cbranch_scc1 .Lfb_slow_1
	buffer_inv sc1
	v_add_u32_e32 v3, 1, v3
	v_mov_b32_e32 v4, 0x23ffc
	ds_write_b32 v4, v3
	v_mul_lo_u32 v5, v3, v0
	s_getreg_b32 s8, hwreg(HW_REG_XCC_ID, 0, 4)
	s_and_b32 s8, s8, 7
	s_lshl_b32 s8, s8, 8
	s_add_u32 s8, s8, 0x3680
	s_add_u32 s4, s92, 0x510000
	s_addc_u32 s5, s93, 0
	v_mov_b32_e32 v6, s8
	v_mov_b32_e32 v7, 1
	global_atomic_add v6, v7, s[4:5]
	s_mov_b32 s9, 0
